# P1 filter-GEMM epilogue de-serialised: the 32 per-row bias loads issued together and waited once instead of a vmcnt(0) per element (which also waited on the previous short store)
# baseline (speedup 1.0000x reference)
.LBB0_277:
	s_ashr_i32 s0, s82, 31
	s_lshr_b32 s0, s0, 27
	s_add_i32 s0, s82, s0
	s_ashr_i32 s4, s0, 5
	s_andn2_b32 s0, s0, 31
	s_ashr_i32 s5, s4, 31
	s_sub_i32 s0, s82, s0
	s_lshl_b64 s[8:9], s[4:5], 15
	s_add_u32 s8, s3, s8
	s_addc_u32 s9, s12, s9
	s_ashr_i32 s1, s0, 31
	s_lshl_b64 s[10:11], s[0:1], 14
	s_add_u32 s10, s13, s10
	s_getreg_b32 s1, hwreg(HW_REG_HW_ID, 0, 6)
	s_addc_u32 s11, s14, s11
	s_lshl_b32 s1, s1, 2
	s_and_b32 s1, s1, 0xfc
	s_add_i32 s1, s1, 0
	s_add_i32 s1, s1, 0x256c0
	v_mov_b32_e32 v0, s1
	ds_read_b32 v0, v0
	v_mbcnt_lo_u32_b32 v8, -1, 0
	v_mbcnt_hi_u32_b32 v8, -1, v8
	s_lshl_b32 s0, s0, 7
	v_and_b32_e32 v88, 31, v8
	v_bfe_u32 v70, v8, 5, 1
	s_waitcnt lgkmcnt(0)
	v_readfirstlane_b32 s1, v0
	v_lshlrev_b32_e32 v128, 2, v70
	s_nop 0
	v_lshl_add_u32 v9, s1, 6, v8
	v_ashrrev_i32_e32 v0, 3, v9
	v_ashrrev_i32_e32 v1, 31, v0
	v_lshlrev_b64 v[2:3], 7, v[0:1]
	v_lshlrev_b32_e32 v1, 4, v8
	v_lshl_add_u64 v[4:5], s[8:9], 0, v[2:3]
	v_and_b32_e32 v64, 0x70, v1
	v_lshl_add_u64 v[4:5], v[4:5], 0, v[64:65]
	v_add_co_u32_e32 v6, vcc, s24, v4
	v_lshl_add_u64 v[2:3], s[10:11], 0, v[2:3]
	s_nop 0
	v_addc_co_u32_e32 v7, vcc, 0, v5, vcc
	global_load_dwordx4 v[72:75], v[4:5], off
	global_load_dwordx4 v[76:79], v[6:7], off
	v_add_co_u32_e32 v6, vcc, s25, v4
	v_lshl_add_u64 v[2:3], v[2:3], 0, v[64:65]
	s_nop 0
	v_addc_co_u32_e32 v7, vcc, 0, v5, vcc
	v_add_co_u32_e32 v4, vcc, s26, v4
	v_ashrrev_i32_e32 v1, 1, v9
	s_nop 0
	v_addc_co_u32_e32 v5, vcc, 0, v5, vcc
	global_load_dwordx4 v[80:83], v[6:7], off
	global_load_dwordx4 v[84:87], v[4:5], off
	global_load_dwordx4 v[92:95], v[2:3], off
	v_add_co_u32_e32 v2, vcc, s24, v2
	v_and_b32_e32 v71, 0xffffffc0, v1
	s_nop 0
	v_addc_co_u32_e32 v3, vcc, 0, v3, vcc
	global_load_dwordx4 v[96:99], v[2:3], off
	v_mul_lo_u32 v0, v0, s15
	v_or_b32_e32 v1, v71, v88
	v_lshlrev_b32_e32 v4, 4, v70
	v_add3_u32 v64, v0, v64, 0
	v_mul_lo_u32 v0, v1, s15
	v_add3_u32 v91, v0, v4, 0
	v_and_b32_e32 v89, 64, v9
	v_or_b32_e32 v5, v89, v88
	v_mul_u32_u24_e32 v5, 0x90, v5
	v_add3_u32 v116, v4, v5, 0
	v_lshl_add_u32 v129, s4, 8, v71
	s_waitcnt vmcnt(5)
	ds_write_b128 v64, v[72:75]
	s_waitcnt vmcnt(1)
	ds_write_b128 v64, v[92:95] offset:36864
	ds_write_b128 v64, v[76:79] offset:9216
	ds_write_b128 v64, v[80:83] offset:18432
	ds_write_b128 v64, v[84:87] offset:27648
	s_waitcnt vmcnt(0)
	ds_write_b128 v64, v[96:99] offset:46080
	s_waitcnt lgkmcnt(0)
	s_barrier
	ds_read_b128 v[0:3], v91
	ds_read_b128 v[4:7], v116 offset:36864
	ds_read_b128 v[66:69], v91 offset:32
	ds_read_b128 v[100:103], v116 offset:36896
	ds_read_b128 v[8:11], v116 offset:41472
	ds_read_b128 v[104:107], v116 offset:41504
	s_waitcnt lgkmcnt(4)
	v_mfma_f32_32x32x16_bf16 v[48:63], v[0:3], v[4:7], 0
	s_waitcnt lgkmcnt(1)
	v_mfma_f32_32x32x16_bf16 v[32:47], v[0:3], v[8:11], 0
	ds_read_b128 v[0:3], v91 offset:4608
	ds_read_b128 v[108:111], v91 offset:4640
	s_waitcnt lgkmcnt(1)
	v_mfma_f32_32x32x16_bf16 v[16:31], v[0:3], v[4:7], 0
	v_mfma_f32_32x32x16_bf16 v[0:15], v[0:3], v[8:11], 0
	v_mfma_f32_32x32x16_bf16 v[48:63], v[66:69], v[100:103], v[48:63]
	v_mfma_f32_32x32x16_bf16 v[32:47], v[66:69], v[104:107], v[32:47]
	s_waitcnt lgkmcnt(0)
	v_mfma_f32_32x32x16_bf16 v[16:31], v[108:111], v[100:103], v[16:31]
	v_mfma_f32_32x32x16_bf16 v[0:15], v[108:111], v[104:107], v[0:15]
	ds_read_b128 v[66:69], v91 offset:64
	ds_read_b128 v[100:103], v116 offset:36928
	ds_read_b128 v[104:107], v91 offset:96
	ds_read_b128 v[108:111], v116 offset:36960
	ds_read_b128 v[112:115], v116 offset:41536
	ds_read_b128 v[116:119], v116 offset:41568
	ds_read_b128 v[120:123], v91 offset:4672
	ds_read_b128 v[124:127], v91 offset:4704
	ds_write_b128 v64, v[72:75] offset:55296
	ds_write_b128 v64, v[76:79] offset:64512
	v_bitop3_b32 v72, v129, s27, v128 bitop3:0xc8
	v_cvt_f32_u32_e32 v74, v72
	s_waitcnt lgkmcnt(8)
	v_mfma_f32_32x32x16_bf16 v[48:63], v[66:69], v[100:103], v[48:63]
	v_and_b32_e32 v73, 0x400, v129
	s_waitcnt lgkmcnt(5)
	v_mfma_f32_32x32x16_bf16 v[32:47], v[66:69], v[112:115], v[32:47]
	v_or_b32_e32 v68, v129, v128
	v_ashrrev_i32_e32 v69, 31, v68
	v_add_u32_e32 v66, 0xd800, v64
	v_lshl_add_u64 v[70:71], v[68:69], 2, s[50:51]
	v_add_u32_e32 v67, 0x16800, v64
	ds_write_b128 v66, v[80:83] offset:18432
	ds_write_b128 v66, v[84:87] offset:27648
	ds_write_b128 v67, v[92:95]
	ds_write_b128 v67, v[96:99] offset:9216
	s_waitcnt lgkmcnt(0)
	s_barrier
	global_load_dword v200, v[70:71], off
	global_load_dword v201, v[70:71], off offset:4
	global_load_dword v202, v[70:71], off offset:8
	global_load_dword v203, v[70:71], off offset:12
	global_load_dword v204, v[70:71], off offset:32
	global_load_dword v205, v[70:71], off offset:36
	global_load_dword v206, v[70:71], off offset:40
	global_load_dword v207, v[70:71], off offset:44
	global_load_dword v208, v[70:71], off offset:64
	global_load_dword v209, v[70:71], off offset:68
	global_load_dword v210, v[70:71], off offset:72
	global_load_dword v211, v[70:71], off offset:76
	global_load_dword v212, v[70:71], off offset:96
	global_load_dword v213, v[70:71], off offset:100
	global_load_dword v214, v[70:71], off offset:104
	global_load_dword v215, v[70:71], off offset:108
	global_load_dword v216, v[70:71], off offset:128
	global_load_dword v217, v[70:71], off offset:132
	global_load_dword v218, v[70:71], off offset:136
	global_load_dword v219, v[70:71], off offset:140
	global_load_dword v220, v[70:71], off offset:160
	global_load_dword v221, v[70:71], off offset:164
	global_load_dword v222, v[70:71], off offset:168
	global_load_dword v223, v[70:71], off offset:172
	global_load_dword v224, v[70:71], off offset:192
	global_load_dword v225, v[70:71], off offset:196
	global_load_dword v226, v[70:71], off offset:200
	global_load_dword v227, v[70:71], off offset:204
	global_load_dword v228, v[70:71], off offset:224
	global_load_dword v229, v[70:71], off offset:228
	global_load_dword v230, v[70:71], off offset:232
	global_load_dword v231, v[70:71], off offset:236
	v_mfma_f32_32x32x16_bf16 v[16:31], v[120:123], v[100:103], v[16:31]
	v_or3_b32 v66, v88, s0, v89
	v_cvt_f32_i32_e32 v64, v66
	v_fmamk_f32 v94, v74, 0xbc44ade8, v90
	v_ashrrev_i32_e32 v69, 1, v129
	v_and_b32_e32 v69, 0xfffffc00, v69
	v_mul_f32_e32 v91, 0xb9800801, v64
	v_mul_f32_e64 v64, v91, |v94|
	v_mfma_f32_32x32x16_bf16 v[0:15], v[120:123], v[112:115], v[0:15]
	v_mul_f32_e32 v64, 0x3fb8aa3b, v64
	v_exp_f32_e32 v64, v64
	v_or_b32_e32 v72, v69, v72
	v_cmp_ne_u32_e64 s[0:1], 0, v73
	v_ashrrev_i32_e32 v73, 31, v72
	v_lshlrev_b64 v[72:73], 14, v[72:73]
	v_cmp_ne_u32_e64 s[4:5], 0, v66
	v_mfma_f32_32x32x16_bf16 v[48:63], v[104:107], v[108:111], v[48:63]
	v_ashrrev_i32_e32 v67, 31, v66
	v_lshl_add_u64 v[72:73], s[6:7], 0, v[72:73]
	v_mfma_f32_32x32x16_bf16 v[32:47], v[104:107], v[116:119], v[32:47]
	s_waitcnt vmcnt(0)
	s_nop 7
	v_add_f32_e32 v48, v48, v200
	v_mfma_f32_32x32x16_bf16 v[16:31], v[124:127], v[108:111], v[16:31]
	v_mul_f32_e32 v48, v64, v48
	v_mfma_f32_32x32x16_bf16 v[0:15], v[124:127], v[116:119], v[0:15]
	s_and_saveexec_b64 s[8:9], s[0:1]
	s_xor_b64 s[8:9], exec, s[8:9]
	s_cbranch_execz .LBB0_283
	s_and_saveexec_b64 s[10:11], s[4:5]
	s_xor_b64 s[10:11], exec, s[10:11]
	s_cbranch_execz .LBB0_280
	v_lshl_add_u64 v[74:75], v[66:67], 1, v[72:73]
	v_add_co_u32_e32 v74, vcc, 0x2000, v74
	v_cvt_pk_bf16_f32 v48, v48, s0
	s_nop 0
	v_addc_co_u32_e32 v75, vcc, 0, v75, vcc
	global_store_short v[74:75], v48, off

.LBB0_285:
	s_or_b64 exec, exec, s[8:9]
	v_bitop3_b32 v48, v68, s28, 1 bitop3:0xc8
	v_cvt_f32_u32_e32 v75, v48
	v_or_b32_e32 v74, v48, v69
	v_fmamk_f32 v96, v75, 0xbc44ade8, v90
	v_mul_f32_e64 v48, v91, |v96|
	v_mul_f32_e32 v48, 0x3fb8aa3b, v48
	v_exp_f32_e32 v48, v48
	v_ashrrev_i32_e32 v75, 31, v74
	v_lshlrev_b64 v[74:75], 14, v[74:75]
	v_lshl_add_u64 v[74:75], s[6:7], 0, v[74:75]
	v_add_f32_e32 v49, v49, v201
	v_mul_f32_e32 v48, v48, v49
	s_and_saveexec_b64 s[8:9], s[0:1]
	s_xor_b64 s[8:9], exec, s[8:9]
	s_cbranch_execz .LBB0_291
	s_and_saveexec_b64 s[10:11], s[4:5]
	s_xor_b64 s[10:11], exec, s[10:11]
	s_cbranch_execz .LBB0_288
	v_cvt_pk_bf16_f32 v76, v48, s0
	v_lshl_add_u64 v[48:49], v[66:67], 1, v[74:75]
	v_add_co_u32_e32 v48, vcc, 0x2000, v48
	s_nop 1
	v_addc_co_u32_e32 v49, vcc, 0, v49, vcc
	global_store_short v[48:49], v76, off

.LBB0_293:
	s_or_b64 exec, exec, s[8:9]
	v_bitop3_b32 v48, v68, s29, 2 bitop3:0xc8
	v_cvt_f32_u32_e32 v49, v48
	v_or_b32_e32 v48, v48, v69
	v_fmamk_f32 v98, v49, 0xbc44ade8, v90
	v_mul_f32_e64 v49, v91, |v98|
	v_mul_f32_e32 v49, 0x3fb8aa3b, v49
	v_exp_f32_e32 v78, v49
	v_ashrrev_i32_e32 v49, 31, v48
	v_lshlrev_b64 v[76:77], 14, v[48:49]
	v_lshl_add_u64 v[76:77], s[6:7], 0, v[76:77]
	v_add_f32_e32 v48, v50, v202
	v_mul_f32_e32 v48, v78, v48
	s_and_saveexec_b64 s[8:9], s[0:1]
	s_xor_b64 s[8:9], exec, s[8:9]
	s_cbranch_execz .LBB0_299
	s_and_saveexec_b64 s[10:11], s[4:5]
	s_xor_b64 s[10:11], exec, s[10:11]
	s_cbranch_execz .LBB0_296
	v_cvt_pk_bf16_f32 v50, v48, s0
	v_lshl_add_u64 v[48:49], v[66:67], 1, v[76:77]
	v_add_co_u32_e32 v48, vcc, 0x2000, v48
	s_nop 1
	v_addc_co_u32_e32 v49, vcc, 0, v49, vcc
	global_store_short v[48:49], v50, off

.LBB0_301:
	s_or_b64 exec, exec, s[8:9]
	v_bitop3_b32 v48, v68, s30, 3 bitop3:0xc8
	v_cvt_f32_u32_e32 v49, v48
	v_or_b32_e32 v48, v48, v69
	v_fmamk_f32 v100, v49, 0xbc44ade8, v90
	v_mul_f32_e64 v49, v91, |v100|
	v_mul_f32_e32 v49, 0x3fb8aa3b, v49
	v_exp_f32_e32 v50, v49
	v_ashrrev_i32_e32 v49, 31, v48
	v_lshlrev_b64 v[78:79], 14, v[48:49]
	v_add_f32_e32 v48, v51, v203
	v_mul_f32_e32 v48, v50, v48
	v_lshl_add_u64 v[50:51], s[6:7], 0, v[78:79]
	s_and_saveexec_b64 s[8:9], s[0:1]
	s_xor_b64 s[8:9], exec, s[8:9]
	s_cbranch_execz .LBB0_307
	s_and_saveexec_b64 s[10:11], s[4:5]
	s_xor_b64 s[10:11], exec, s[10:11]
	s_cbranch_execz .LBB0_304
	v_cvt_pk_bf16_f32 v78, v48, s0
	v_lshl_add_u64 v[48:49], v[66:67], 1, v[50:51]
	v_add_co_u32_e32 v48, vcc, 0x2000, v48
	s_nop 1
	v_addc_co_u32_e32 v49, vcc, 0, v49, vcc
	global_store_short v[48:49], v78, off

.LBB0_309:
	s_or_b64 exec, exec, s[8:9]
	v_bitop3_b32 v48, v68, s31, 8 bitop3:0xc8
	v_cvt_f32_u32_e32 v49, v48
	v_or_b32_e32 v48, v48, v69
	v_fmamk_f32 v102, v49, 0xbc44ade8, v90
	v_mul_f32_e64 v49, v91, |v102|
	v_mul_f32_e32 v49, 0x3fb8aa3b, v49
	v_exp_f32_e32 v80, v49
	v_ashrrev_i32_e32 v49, 31, v48
	v_lshlrev_b64 v[78:79], 14, v[48:49]
	v_lshl_add_u64 v[78:79], s[6:7], 0, v[78:79]
	v_add_f32_e32 v48, v52, v204
	v_mul_f32_e32 v48, v80, v48
	s_and_saveexec_b64 s[8:9], s[0:1]
	s_xor_b64 s[8:9], exec, s[8:9]
	s_cbranch_execz .LBB0_315
	s_and_saveexec_b64 s[10:11], s[4:5]
	s_xor_b64 s[10:11], exec, s[10:11]
	s_cbranch_execz .LBB0_312
	v_cvt_pk_bf16_f32 v52, v48, s0
	v_lshl_add_u64 v[48:49], v[66:67], 1, v[78:79]
	v_add_co_u32_e32 v48, vcc, 0x2000, v48
	s_nop 1
	v_addc_co_u32_e32 v49, vcc, 0, v49, vcc
	global_store_short v[48:49], v52, off

.LBB0_317:
	s_or_b64 exec, exec, s[8:9]
	v_bitop3_b32 v48, v68, s33, 9 bitop3:0xc8
	v_cvt_f32_u32_e32 v49, v48
	v_or_b32_e32 v48, v48, v69
	v_fmamk_f32 v104, v49, 0xbc44ade8, v90
	v_mul_f32_e64 v49, v91, |v104|
	v_mul_f32_e32 v49, 0x3fb8aa3b, v49
	v_exp_f32_e32 v52, v49
	v_ashrrev_i32_e32 v49, 31, v48
	v_lshlrev_b64 v[80:81], 14, v[48:49]
	v_add_f32_e32 v48, v53, v205
	v_mul_f32_e32 v48, v52, v48
	v_lshl_add_u64 v[52:53], s[6:7], 0, v[80:81]
	s_and_saveexec_b64 s[8:9], s[0:1]
	s_xor_b64 s[8:9], exec, s[8:9]
	s_cbranch_execz .LBB0_323
	s_and_saveexec_b64 s[10:11], s[4:5]
	s_xor_b64 s[10:11], exec, s[10:11]
	s_cbranch_execz .LBB0_320
	v_cvt_pk_bf16_f32 v80, v48, s0
	v_lshl_add_u64 v[48:49], v[66:67], 1, v[52:53]
	v_add_co_u32_e32 v48, vcc, 0x2000, v48
	s_nop 1
	v_addc_co_u32_e32 v49, vcc, 0, v49, vcc
	global_store_short v[48:49], v80, off

.LBB0_325:
	s_or_b64 exec, exec, s[8:9]
	v_bitop3_b32 v48, v68, s40, 10 bitop3:0xc8
	v_cvt_f32_u32_e32 v49, v48
	v_or_b32_e32 v48, v48, v69
	v_fmamk_f32 v106, v49, 0xbc44ade8, v90
	v_mul_f32_e64 v49, v91, |v106|
	v_mul_f32_e32 v49, 0x3fb8aa3b, v49
	v_exp_f32_e32 v82, v49
	v_ashrrev_i32_e32 v49, 31, v48
	v_lshlrev_b64 v[80:81], 14, v[48:49]
	v_lshl_add_u64 v[80:81], s[6:7], 0, v[80:81]
	v_add_f32_e32 v48, v54, v206
	v_mul_f32_e32 v48, v82, v48
	s_and_saveexec_b64 s[8:9], s[0:1]
	s_xor_b64 s[8:9], exec, s[8:9]
	s_cbranch_execz .LBB0_331
	s_and_saveexec_b64 s[10:11], s[4:5]
	s_xor_b64 s[10:11], exec, s[10:11]
	s_cbranch_execz .LBB0_328
	v_cvt_pk_bf16_f32 v54, v48, s0
	v_lshl_add_u64 v[48:49], v[66:67], 1, v[80:81]
	v_add_co_u32_e32 v48, vcc, 0x2000, v48
	s_nop 1
	v_addc_co_u32_e32 v49, vcc, 0, v49, vcc
	global_store_short v[48:49], v54, off

.LBB0_333:
	s_or_b64 exec, exec, s[8:9]
	v_bitop3_b32 v48, v68, s41, 11 bitop3:0xc8
	v_cvt_f32_u32_e32 v49, v48
	v_or_b32_e32 v48, v48, v69
	v_fmamk_f32 v108, v49, 0xbc44ade8, v90
	v_mul_f32_e64 v49, v91, |v108|
	v_mul_f32_e32 v49, 0x3fb8aa3b, v49
	v_exp_f32_e32 v54, v49
	v_ashrrev_i32_e32 v49, 31, v48
	v_lshlrev_b64 v[82:83], 14, v[48:49]
	v_add_f32_e32 v48, v55, v207
	v_mul_f32_e32 v48, v54, v48
	v_lshl_add_u64 v[54:55], s[6:7], 0, v[82:83]
	s_and_saveexec_b64 s[8:9], s[0:1]
	s_xor_b64 s[8:9], exec, s[8:9]
	s_cbranch_execz .LBB0_339
	s_and_saveexec_b64 s[10:11], s[4:5]
	s_xor_b64 s[10:11], exec, s[10:11]
	s_cbranch_execz .LBB0_336
	v_cvt_pk_bf16_f32 v82, v48, s0
	v_lshl_add_u64 v[48:49], v[66:67], 1, v[54:55]
	v_add_co_u32_e32 v48, vcc, 0x2000, v48
	s_nop 1
	v_addc_co_u32_e32 v49, vcc, 0, v49, vcc
	global_store_short v[48:49], v82, off

.LBB0_341:
	s_or_b64 exec, exec, s[8:9]
	v_bitop3_b32 v48, v68, s42, 16 bitop3:0xc8
	v_cvt_f32_u32_e32 v49, v48
	v_or_b32_e32 v48, v48, v69
	v_fmamk_f32 v110, v49, 0xbc44ade8, v90
	v_mul_f32_e64 v49, v91, |v110|
	v_mul_f32_e32 v49, 0x3fb8aa3b, v49
	v_exp_f32_e32 v84, v49
	v_ashrrev_i32_e32 v49, 31, v48
	v_lshlrev_b64 v[82:83], 14, v[48:49]
	v_lshl_add_u64 v[82:83], s[6:7], 0, v[82:83]
	v_add_f32_e32 v48, v56, v208
	v_mul_f32_e32 v48, v84, v48
	s_and_saveexec_b64 s[8:9], s[0:1]
	s_xor_b64 s[8:9], exec, s[8:9]
	s_cbranch_execz .LBB0_347
	s_and_saveexec_b64 s[10:11], s[4:5]
	s_xor_b64 s[10:11], exec, s[10:11]
	s_cbranch_execz .LBB0_344
	v_cvt_pk_bf16_f32 v56, v48, s0
	v_lshl_add_u64 v[48:49], v[66:67], 1, v[82:83]
	v_add_co_u32_e32 v48, vcc, 0x2000, v48
	s_nop 1
	v_addc_co_u32_e32 v49, vcc, 0, v49, vcc
	global_store_short v[48:49], v56, off

.LBB0_349:
	s_or_b64 exec, exec, s[8:9]
	v_bitop3_b32 v48, v68, s43, 17 bitop3:0xc8
	v_cvt_f32_u32_e32 v49, v48
	v_or_b32_e32 v48, v48, v69
	v_fmamk_f32 v112, v49, 0xbc44ade8, v90
	v_mul_f32_e64 v49, v91, |v112|
	v_mul_f32_e32 v49, 0x3fb8aa3b, v49
	v_exp_f32_e32 v56, v49
	v_ashrrev_i32_e32 v49, 31, v48
	v_lshlrev_b64 v[84:85], 14, v[48:49]
	v_add_f32_e32 v48, v57, v209
	v_mul_f32_e32 v48, v56, v48
	v_lshl_add_u64 v[56:57], s[6:7], 0, v[84:85]
	s_and_saveexec_b64 s[8:9], s[0:1]
	s_xor_b64 s[8:9], exec, s[8:9]
	s_cbranch_execz .LBB0_355
	s_and_saveexec_b64 s[10:11], s[4:5]
	s_xor_b64 s[10:11], exec, s[10:11]
	s_cbranch_execz .LBB0_352
	v_cvt_pk_bf16_f32 v84, v48, s0
	v_lshl_add_u64 v[48:49], v[66:67], 1, v[56:57]
	v_add_co_u32_e32 v48, vcc, 0x2000, v48
	s_nop 1
	v_addc_co_u32_e32 v49, vcc, 0, v49, vcc
	global_store_short v[48:49], v84, off

.LBB0_357:
	s_or_b64 exec, exec, s[8:9]
	v_bitop3_b32 v48, v68, s44, 18 bitop3:0xc8
	v_cvt_f32_u32_e32 v49, v48
	v_or_b32_e32 v48, v48, v69
	v_fmamk_f32 v114, v49, 0xbc44ade8, v90
	v_mul_f32_e64 v49, v91, |v114|
	v_mul_f32_e32 v49, 0x3fb8aa3b, v49
	v_exp_f32_e32 v86, v49
	v_ashrrev_i32_e32 v49, 31, v48
	v_lshlrev_b64 v[84:85], 14, v[48:49]
	v_lshl_add_u64 v[84:85], s[6:7], 0, v[84:85]
	v_add_f32_e32 v48, v58, v210
	v_mul_f32_e32 v48, v86, v48
	s_and_saveexec_b64 s[8:9], s[0:1]
	s_xor_b64 s[8:9], exec, s[8:9]
	s_cbranch_execz .LBB0_363
	s_and_saveexec_b64 s[10:11], s[4:5]
	s_xor_b64 s[10:11], exec, s[10:11]
	s_cbranch_execz .LBB0_360
	v_cvt_pk_bf16_f32 v58, v48, s0
	v_lshl_add_u64 v[48:49], v[66:67], 1, v[84:85]
	v_add_co_u32_e32 v48, vcc, 0x2000, v48
	s_nop 1
	v_addc_co_u32_e32 v49, vcc, 0, v49, vcc
	global_store_short v[48:49], v58, off

.LBB0_365:
	s_or_b64 exec, exec, s[8:9]
	v_bitop3_b32 v48, v68, s45, 19 bitop3:0xc8
	v_cvt_f32_u32_e32 v49, v48
	v_or_b32_e32 v48, v48, v69
	v_fmamk_f32 v116, v49, 0xbc44ade8, v90
	v_mul_f32_e64 v49, v91, |v116|
	v_mul_f32_e32 v49, 0x3fb8aa3b, v49
	v_exp_f32_e32 v58, v49
	v_ashrrev_i32_e32 v49, 31, v48
	v_lshlrev_b64 v[86:87], 14, v[48:49]
	v_add_f32_e32 v48, v59, v211
	v_mul_f32_e32 v48, v58, v48
	v_lshl_add_u64 v[58:59], s[6:7], 0, v[86:87]
	s_and_saveexec_b64 s[8:9], s[0:1]
	s_xor_b64 s[8:9], exec, s[8:9]
	s_cbranch_execz .LBB0_371
	s_and_saveexec_b64 s[10:11], s[4:5]
	s_xor_b64 s[10:11], exec, s[10:11]
	s_cbranch_execz .LBB0_368
	v_cvt_pk_bf16_f32 v86, v48, s0
	v_lshl_add_u64 v[48:49], v[66:67], 1, v[58:59]
	v_add_co_u32_e32 v48, vcc, 0x2000, v48
	s_nop 1
	v_addc_co_u32_e32 v49, vcc, 0, v49, vcc
	global_store_short v[48:49], v86, off

.LBB0_373:
	s_or_b64 exec, exec, s[8:9]
	v_bitop3_b32 v48, v68, s46, 24 bitop3:0xc8
	v_cvt_f32_u32_e32 v49, v48
	v_or_b32_e32 v48, v48, v69
	v_fmamk_f32 v118, v49, 0xbc44ade8, v90
	v_mul_f32_e64 v49, v91, |v118|
	v_mul_f32_e32 v49, 0x3fb8aa3b, v49
	v_exp_f32_e32 v88, v49
	v_ashrrev_i32_e32 v49, 31, v48
	v_lshlrev_b64 v[86:87], 14, v[48:49]
	v_lshl_add_u64 v[86:87], s[6:7], 0, v[86:87]
	v_add_f32_e32 v48, v60, v212
	v_mul_f32_e32 v48, v88, v48
	s_and_saveexec_b64 s[8:9], s[0:1]
	s_xor_b64 s[8:9], exec, s[8:9]
	s_cbranch_execz .LBB0_379
	s_and_saveexec_b64 s[10:11], s[4:5]
	s_xor_b64 s[10:11], exec, s[10:11]
	s_cbranch_execz .LBB0_376
	v_cvt_pk_bf16_f32 v60, v48, s0
	v_lshl_add_u64 v[48:49], v[66:67], 1, v[86:87]
	v_add_co_u32_e32 v48, vcc, 0x2000, v48
	s_nop 1
	v_addc_co_u32_e32 v49, vcc, 0, v49, vcc
	global_store_short v[48:49], v60, off

.LBB0_381:
	s_or_b64 exec, exec, s[8:9]
	v_bitop3_b32 v48, v68, s47, 25 bitop3:0xc8
	v_cvt_f32_u32_e32 v49, v48
	v_or_b32_e32 v48, v48, v69
	v_fmamk_f32 v120, v49, 0xbc44ade8, v90
	v_mul_f32_e64 v49, v91, |v120|
	v_mul_f32_e32 v49, 0x3fb8aa3b, v49
	v_exp_f32_e32 v60, v49
	v_ashrrev_i32_e32 v49, 31, v48
	v_lshlrev_b64 v[88:89], 14, v[48:49]
	v_add_f32_e32 v48, v61, v213
	v_mul_f32_e32 v48, v60, v48
	v_lshl_add_u64 v[60:61], s[6:7], 0, v[88:89]
	s_and_saveexec_b64 s[8:9], s[0:1]
	s_xor_b64 s[8:9], exec, s[8:9]
	s_cbranch_execz .LBB0_387
	s_and_saveexec_b64 s[10:11], s[4:5]
	s_xor_b64 s[10:11], exec, s[10:11]
	s_cbranch_execz .LBB0_384
	v_cvt_pk_bf16_f32 v88, v48, s0
	v_lshl_add_u64 v[48:49], v[66:67], 1, v[60:61]
	v_add_co_u32_e32 v48, vcc, 0x2000, v48
	s_nop 1
	v_addc_co_u32_e32 v49, vcc, 0, v49, vcc
	global_store_short v[48:49], v88, off

.LBB0_389:
	s_or_b64 exec, exec, s[8:9]
	v_bitop3_b32 v48, v68, s48, 26 bitop3:0xc8
	v_cvt_f32_u32_e32 v49, v48
	v_or_b32_e32 v48, v48, v69
	v_fmamk_f32 v122, v49, 0xbc44ade8, v90
	v_mul_f32_e64 v49, v91, |v122|
	v_mul_f32_e32 v49, 0x3fb8aa3b, v49
	v_exp_f32_e32 v92, v49
	v_ashrrev_i32_e32 v49, 31, v48
	v_lshlrev_b64 v[88:89], 14, v[48:49]
	v_lshl_add_u64 v[88:89], s[6:7], 0, v[88:89]
	v_add_f32_e32 v48, v62, v214
	v_mul_f32_e32 v48, v92, v48
	s_and_saveexec_b64 s[8:9], s[0:1]
	s_xor_b64 s[8:9], exec, s[8:9]
	s_cbranch_execz .LBB0_395
	s_and_saveexec_b64 s[10:11], s[4:5]
	s_xor_b64 s[10:11], exec, s[10:11]
	s_cbranch_execz .LBB0_392
	v_cvt_pk_bf16_f32 v62, v48, s0
	v_lshl_add_u64 v[48:49], v[66:67], 1, v[88:89]
	v_add_co_u32_e32 v48, vcc, 0x2000, v48
	s_nop 1
	v_addc_co_u32_e32 v49, vcc, 0, v49, vcc
	global_store_short v[48:49], v62, off

.LBB0_397:
	s_or_b64 exec, exec, s[8:9]
	v_bitop3_b32 v48, v68, s49, 27 bitop3:0xc8
	v_cvt_f32_u32_e32 v49, v48
	v_or_b32_e32 v48, v48, v69
	v_fmamk_f32 v124, v49, 0xbc44ade8, v90
	v_mul_f32_e64 v49, v91, |v124|
	v_mul_f32_e32 v49, 0x3fb8aa3b, v49
	v_exp_f32_e32 v62, v49
	v_ashrrev_i32_e32 v49, 31, v48
	v_lshlrev_b64 v[126:127], 14, v[48:49]
	v_add_f32_e32 v48, v63, v215
	v_mul_f32_e32 v48, v62, v48
	v_lshl_add_u64 v[62:63], s[6:7], 0, v[126:127]
	s_and_saveexec_b64 s[8:9], s[0:1]
	s_xor_b64 s[8:9], exec, s[8:9]
	s_cbranch_execz .LBB0_403
	s_and_saveexec_b64 s[10:11], s[4:5]
	s_xor_b64 s[10:11], exec, s[10:11]
	s_cbranch_execz .LBB0_400
	v_cvt_pk_bf16_f32 v92, v48, s0
	v_lshl_add_u64 v[48:49], v[66:67], 1, v[62:63]
	v_add_co_u32_e32 v48, vcc, 0x2000, v48
	s_nop 1
	v_addc_co_u32_e32 v49, vcc, 0, v49, vcc
	global_store_short v[48:49], v92, off

.LBB0_405:
	s_or_b64 exec, exec, s[8:9]
	v_or_b32_e32 v48, 32, v66
	v_cvt_f32_i32_e32 v48, v48
	v_add_f32_e32 v32, v32, v200
	v_mul_f32_e32 v92, 0xb9800801, v48
	v_mul_f32_e64 v48, v92, |v94|
	v_mul_f32_e32 v48, 0x3fb8aa3b, v48
	v_exp_f32_e32 v48, v48
	s_nop 0
	v_mul_f32_e32 v32, v48, v32
	v_cvt_pk_bf16_f32 v32, v32, s0
	s_and_saveexec_b64 s[8:9], s[0:1]
	s_xor_b64 s[8:9], exec, s[8:9]
	s_cbranch_execz .LBB0_407
	v_lshl_add_u64 v[48:49], v[66:67], 1, v[72:73]
	v_add_co_u32_e32 v48, vcc, 0x2000, v48
	s_nop 1
	v_addc_co_u32_e32 v49, vcc, 0, v49, vcc
	global_store_short v[48:49], v32, off offset:64

.LBB0_409:
	s_or_b64 exec, exec, s[8:9]
	v_mul_f32_e64 v32, v92, |v96|
	v_mul_f32_e32 v32, 0x3fb8aa3b, v32
	v_exp_f32_e32 v32, v32
	v_add_f32_e32 v33, v33, v201
	v_mul_f32_e32 v32, v32, v33
	v_cvt_pk_bf16_f32 v32, v32, s0
	s_and_saveexec_b64 s[8:9], s[0:1]
	s_xor_b64 s[8:9], exec, s[8:9]
	s_cbranch_execz .LBB0_411
	v_lshl_add_u64 v[72:73], v[66:67], 1, v[74:75]
	v_add_co_u32_e32 v72, vcc, 0x2000, v72
	s_nop 1
	v_addc_co_u32_e32 v73, vcc, 0, v73, vcc
	global_store_short v[72:73], v32, off offset:64

.LBB0_413:
	s_or_b64 exec, exec, s[8:9]
	v_mul_f32_e64 v32, v92, |v98|
	v_mul_f32_e32 v32, 0x3fb8aa3b, v32
	v_exp_f32_e32 v32, v32
	v_add_f32_e32 v33, v34, v202
	v_mul_f32_e32 v32, v32, v33
	v_cvt_pk_bf16_f32 v32, v32, s0
	s_and_saveexec_b64 s[8:9], s[0:1]
	s_xor_b64 s[8:9], exec, s[8:9]
	s_cbranch_execz .LBB0_415
	v_lshl_add_u64 v[72:73], v[66:67], 1, v[76:77]
	v_add_co_u32_e32 v72, vcc, 0x2000, v72
	s_nop 1
	v_addc_co_u32_e32 v73, vcc, 0, v73, vcc
	global_store_short v[72:73], v32, off offset:64

.LBB0_417:
	s_or_b64 exec, exec, s[8:9]
	v_mul_f32_e64 v32, v92, |v100|
	v_mul_f32_e32 v32, 0x3fb8aa3b, v32
	v_exp_f32_e32 v32, v32
	v_add_f32_e32 v33, v35, v203
	v_mul_f32_e32 v32, v32, v33
	v_cvt_pk_bf16_f32 v32, v32, s0
	s_and_saveexec_b64 s[8:9], s[0:1]
	s_xor_b64 s[8:9], exec, s[8:9]
	s_cbranch_execz .LBB0_419
	v_lshl_add_u64 v[34:35], v[66:67], 1, v[50:51]
	v_add_co_u32_e32 v34, vcc, 0x2000, v34
	s_nop 1
	v_addc_co_u32_e32 v35, vcc, 0, v35, vcc
	global_store_short v[34:35], v32, off offset:64

.LBB0_421:
	s_or_b64 exec, exec, s[8:9]
	v_mul_f32_e64 v32, v92, |v102|
	v_mul_f32_e32 v32, 0x3fb8aa3b, v32
	v_exp_f32_e32 v32, v32
	v_add_f32_e32 v33, v36, v204
	v_mul_f32_e32 v32, v32, v33
	v_cvt_pk_bf16_f32 v32, v32, s0
	s_and_saveexec_b64 s[8:9], s[0:1]
	s_xor_b64 s[8:9], exec, s[8:9]
	s_cbranch_execz .LBB0_423
	v_lshl_add_u64 v[34:35], v[66:67], 1, v[78:79]
	v_add_co_u32_e32 v34, vcc, 0x2000, v34
	s_nop 1
	v_addc_co_u32_e32 v35, vcc, 0, v35, vcc
	global_store_short v[34:35], v32, off offset:64

.LBB0_425:
	s_or_b64 exec, exec, s[8:9]
	v_mul_f32_e64 v32, v92, |v104|
	v_mul_f32_e32 v32, 0x3fb8aa3b, v32
	v_exp_f32_e32 v32, v32
	v_add_f32_e32 v33, v37, v205
	v_mul_f32_e32 v32, v32, v33
	v_cvt_pk_bf16_f32 v32, v32, s0
	s_and_saveexec_b64 s[8:9], s[0:1]
	s_xor_b64 s[8:9], exec, s[8:9]
	s_cbranch_execz .LBB0_427
	v_lshl_add_u64 v[34:35], v[66:67], 1, v[52:53]
	v_add_co_u32_e32 v34, vcc, 0x2000, v34
	s_nop 1
	v_addc_co_u32_e32 v35, vcc, 0, v35, vcc
	global_store_short v[34:35], v32, off offset:64

.LBB0_429:
	s_or_b64 exec, exec, s[8:9]
	v_mul_f32_e64 v32, v92, |v106|
	v_mul_f32_e32 v32, 0x3fb8aa3b, v32
	v_exp_f32_e32 v32, v32
	v_add_f32_e32 v33, v38, v206
	v_mul_f32_e32 v32, v32, v33
	v_cvt_pk_bf16_f32 v32, v32, s0
	s_and_saveexec_b64 s[8:9], s[0:1]
	s_xor_b64 s[8:9], exec, s[8:9]
	s_cbranch_execz .LBB0_431
	v_lshl_add_u64 v[34:35], v[66:67], 1, v[80:81]
	v_add_co_u32_e32 v34, vcc, 0x2000, v34
	s_nop 1
	v_addc_co_u32_e32 v35, vcc, 0, v35, vcc
	global_store_short v[34:35], v32, off offset:64

.LBB0_433:
	s_or_b64 exec, exec, s[8:9]
	v_mul_f32_e64 v32, v92, |v108|
	v_mul_f32_e32 v32, 0x3fb8aa3b, v32
	v_exp_f32_e32 v32, v32
	v_add_f32_e32 v33, v39, v207
	v_mul_f32_e32 v32, v32, v33
	v_cvt_pk_bf16_f32 v32, v32, s0
	s_and_saveexec_b64 s[8:9], s[0:1]
	s_xor_b64 s[8:9], exec, s[8:9]
	s_cbranch_execz .LBB0_435
	v_lshl_add_u64 v[34:35], v[66:67], 1, v[54:55]
	v_add_co_u32_e32 v34, vcc, 0x2000, v34
	s_nop 1
	v_addc_co_u32_e32 v35, vcc, 0, v35, vcc
	global_store_short v[34:35], v32, off offset:64

.LBB0_437:
	s_or_b64 exec, exec, s[8:9]
	v_mul_f32_e64 v32, v92, |v110|
	v_mul_f32_e32 v32, 0x3fb8aa3b, v32
	v_exp_f32_e32 v32, v32
	v_add_f32_e32 v33, v40, v208
	v_mul_f32_e32 v32, v32, v33
	v_cvt_pk_bf16_f32 v32, v32, s0
	s_and_saveexec_b64 s[8:9], s[0:1]
	s_xor_b64 s[8:9], exec, s[8:9]
	s_cbranch_execz .LBB0_439
	v_lshl_add_u64 v[34:35], v[66:67], 1, v[82:83]
	v_add_co_u32_e32 v34, vcc, 0x2000, v34
	s_nop 1
	v_addc_co_u32_e32 v35, vcc, 0, v35, vcc
	global_store_short v[34:35], v32, off offset:64

.LBB0_441:
	s_or_b64 exec, exec, s[8:9]
	v_mul_f32_e64 v32, v92, |v112|
	v_mul_f32_e32 v32, 0x3fb8aa3b, v32
	v_exp_f32_e32 v32, v32
	v_add_f32_e32 v33, v41, v209
	v_mul_f32_e32 v32, v32, v33
	v_cvt_pk_bf16_f32 v32, v32, s0
	s_and_saveexec_b64 s[8:9], s[0:1]
	s_xor_b64 s[8:9], exec, s[8:9]
	s_cbranch_execz .LBB0_443
	v_lshl_add_u64 v[34:35], v[66:67], 1, v[56:57]
	v_add_co_u32_e32 v34, vcc, 0x2000, v34
	s_nop 1
	v_addc_co_u32_e32 v35, vcc, 0, v35, vcc
	global_store_short v[34:35], v32, off offset:64

.LBB0_445:
	s_or_b64 exec, exec, s[8:9]
	v_mul_f32_e64 v32, v92, |v114|
	v_mul_f32_e32 v32, 0x3fb8aa3b, v32
	v_exp_f32_e32 v32, v32
	v_add_f32_e32 v33, v42, v210
	v_mul_f32_e32 v32, v32, v33
	v_cvt_pk_bf16_f32 v32, v32, s0
	s_and_saveexec_b64 s[8:9], s[0:1]
	s_xor_b64 s[8:9], exec, s[8:9]
	s_cbranch_execz .LBB0_447
	v_lshl_add_u64 v[34:35], v[66:67], 1, v[84:85]
	v_add_co_u32_e32 v34, vcc, 0x2000, v34
	s_nop 1
	v_addc_co_u32_e32 v35, vcc, 0, v35, vcc
	global_store_short v[34:35], v32, off offset:64

.LBB0_449:
	s_or_b64 exec, exec, s[8:9]
	v_mul_f32_e64 v32, v92, |v116|
	v_mul_f32_e32 v32, 0x3fb8aa3b, v32
	v_exp_f32_e32 v32, v32
	v_add_f32_e32 v33, v43, v211
	v_mul_f32_e32 v32, v32, v33
	v_cvt_pk_bf16_f32 v32, v32, s0
	s_and_saveexec_b64 s[8:9], s[0:1]
	s_xor_b64 s[8:9], exec, s[8:9]
	s_cbranch_execz .LBB0_451
	v_lshl_add_u64 v[34:35], v[66:67], 1, v[58:59]
	v_add_co_u32_e32 v34, vcc, 0x2000, v34
	s_nop 1
	v_addc_co_u32_e32 v35, vcc, 0, v35, vcc
	global_store_short v[34:35], v32, off offset:64

.LBB0_453:
	s_or_b64 exec, exec, s[8:9]
	v_mul_f32_e64 v32, v92, |v118|
	v_mul_f32_e32 v32, 0x3fb8aa3b, v32
	v_exp_f32_e32 v32, v32
	v_add_f32_e32 v33, v44, v212
	v_mul_f32_e32 v32, v32, v33
	v_cvt_pk_bf16_f32 v32, v32, s0
	s_and_saveexec_b64 s[8:9], s[0:1]
	s_xor_b64 s[8:9], exec, s[8:9]
	s_cbranch_execz .LBB0_455
	v_lshl_add_u64 v[34:35], v[66:67], 1, v[86:87]
	v_add_co_u32_e32 v34, vcc, 0x2000, v34
	s_nop 1
	v_addc_co_u32_e32 v35, vcc, 0, v35, vcc
	global_store_short v[34:35], v32, off offset:64

.LBB0_457:
	s_or_b64 exec, exec, s[8:9]
	v_mul_f32_e64 v32, v92, |v120|
	v_mul_f32_e32 v32, 0x3fb8aa3b, v32
	v_exp_f32_e32 v32, v32
	v_add_f32_e32 v33, v45, v213
	v_mul_f32_e32 v32, v32, v33
	v_cvt_pk_bf16_f32 v32, v32, s0
	s_and_saveexec_b64 s[8:9], s[0:1]
	s_xor_b64 s[8:9], exec, s[8:9]
	s_cbranch_execz .LBB0_459
	v_lshl_add_u64 v[34:35], v[66:67], 1, v[60:61]
	v_add_co_u32_e32 v34, vcc, 0x2000, v34
	s_nop 1
	v_addc_co_u32_e32 v35, vcc, 0, v35, vcc
	global_store_short v[34:35], v32, off offset:64

.LBB0_461:
	s_or_b64 exec, exec, s[8:9]
	v_mul_f32_e64 v32, v92, |v122|
	v_mul_f32_e32 v32, 0x3fb8aa3b, v32
	v_exp_f32_e32 v32, v32
	v_add_f32_e32 v33, v46, v214
	v_mul_f32_e32 v32, v32, v33
	v_cvt_pk_bf16_f32 v32, v32, s0
	s_and_saveexec_b64 s[8:9], s[0:1]
	s_xor_b64 s[8:9], exec, s[8:9]
	s_cbranch_execz .LBB0_463
	v_lshl_add_u64 v[34:35], v[66:67], 1, v[88:89]
	v_add_co_u32_e32 v34, vcc, 0x2000, v34
	s_nop 1
	v_addc_co_u32_e32 v35, vcc, 0, v35, vcc
	global_store_short v[34:35], v32, off offset:64

.LBB0_465:
	s_or_b64 exec, exec, s[8:9]
	v_mul_f32_e64 v32, v92, |v124|
	v_mul_f32_e32 v32, 0x3fb8aa3b, v32
	v_exp_f32_e32 v32, v32
	v_add_f32_e32 v33, v47, v215
	v_mul_f32_e32 v32, v32, v33
	v_cvt_pk_bf16_f32 v32, v32, s0
	s_and_saveexec_b64 s[8:9], s[0:1]
	s_xor_b64 s[8:9], exec, s[8:9]
	s_cbranch_execz .LBB0_467
	v_lshl_add_u64 v[34:35], v[66:67], 1, v[62:63]
	v_add_co_u32_e32 v34, vcc, 0x2000, v34
	s_nop 1
	v_addc_co_u32_e32 v35, vcc, 0, v35, vcc
	global_store_short v[34:35], v32, off offset:64

.LBB0_469:
	s_or_b64 exec, exec, s[8:9]
	v_bitop3_b32 v32, v68, s54, 32 bitop3:0xc8
	v_cvt_f32_u32_e32 v33, v32
	v_or_b32_e32 v32, v32, v69
	v_fmamk_f32 v51, v33, 0xbc44ade8, v90
	v_mul_f32_e64 v33, v91, |v51|
	v_mul_f32_e32 v33, 0x3fb8aa3b, v33
	v_exp_f32_e32 v34, v33
	v_ashrrev_i32_e32 v33, 31, v32
	v_lshlrev_b64 v[32:33], 14, v[32:33]
	v_lshl_add_u64 v[32:33], s[6:7], 0, v[32:33]
	v_add_f32_e32 v16, v16, v216
	v_mul_f32_e32 v16, v34, v16
	s_and_saveexec_b64 s[8:9], s[0:1]
	s_xor_b64 s[8:9], exec, s[8:9]
	s_cbranch_execz .LBB0_475
	s_and_saveexec_b64 s[10:11], s[4:5]
	s_xor_b64 s[10:11], exec, s[10:11]
	s_cbranch_execz .LBB0_472
	v_lshl_add_u64 v[34:35], v[66:67], 1, v[32:33]
	v_add_co_u32_e32 v34, vcc, 0x2000, v34
	v_cvt_pk_bf16_f32 v16, v16, s0
	s_nop 0
	v_addc_co_u32_e32 v35, vcc, 0, v35, vcc
	global_store_short v[34:35], v16, off

.LBB0_477:
	s_or_b64 exec, exec, s[8:9]
	v_bitop3_b32 v16, v68, s55, 33 bitop3:0xc8
	v_cvt_f32_u32_e32 v35, v16
	v_or_b32_e32 v34, v16, v69
	v_fmamk_f32 v53, v35, 0xbc44ade8, v90
	v_mul_f32_e64 v16, v91, |v53|
	v_mul_f32_e32 v16, 0x3fb8aa3b, v16
	v_exp_f32_e32 v16, v16
	v_ashrrev_i32_e32 v35, 31, v34
	v_lshlrev_b64 v[36:37], 14, v[34:35]
	v_add_f32_e32 v17, v17, v217
	v_mul_f32_e32 v34, v16, v17
	v_lshl_add_u64 v[16:17], s[6:7], 0, v[36:37]
	s_and_saveexec_b64 s[8:9], s[0:1]
	s_xor_b64 s[8:9], exec, s[8:9]
	s_cbranch_execz .LBB0_483
	s_and_saveexec_b64 s[10:11], s[4:5]
	s_xor_b64 s[10:11], exec, s[10:11]
	s_cbranch_execz .LBB0_480
	v_cvt_pk_bf16_f32 v36, v34, s0
	v_lshl_add_u64 v[34:35], v[66:67], 1, v[16:17]
	v_add_co_u32_e32 v34, vcc, 0x2000, v34
	s_nop 1
	v_addc_co_u32_e32 v35, vcc, 0, v35, vcc
	global_store_short v[34:35], v36, off

.LBB0_485:
	s_or_b64 exec, exec, s[8:9]
	v_bitop3_b32 v34, v68, s58, 34 bitop3:0xc8
	v_cvt_f32_u32_e32 v35, v34
	v_or_b32_e32 v34, v34, v69
	v_fmamk_f32 v55, v35, 0xbc44ade8, v90
	v_mul_f32_e64 v35, v91, |v55|
	v_mul_f32_e32 v35, 0x3fb8aa3b, v35
	v_exp_f32_e32 v36, v35
	v_ashrrev_i32_e32 v35, 31, v34
	v_lshlrev_b64 v[34:35], 14, v[34:35]
	v_lshl_add_u64 v[34:35], s[6:7], 0, v[34:35]
	v_add_f32_e32 v18, v18, v218
	v_mul_f32_e32 v18, v36, v18
	s_and_saveexec_b64 s[8:9], s[0:1]
	s_xor_b64 s[8:9], exec, s[8:9]
	s_cbranch_execz .LBB0_491
	s_and_saveexec_b64 s[10:11], s[4:5]
	s_xor_b64 s[10:11], exec, s[10:11]
	s_cbranch_execz .LBB0_488
	v_lshl_add_u64 v[36:37], v[66:67], 1, v[34:35]
	v_add_co_u32_e32 v36, vcc, 0x2000, v36
	v_cvt_pk_bf16_f32 v18, v18, s0
	s_nop 0
	v_addc_co_u32_e32 v37, vcc, 0, v37, vcc
	global_store_short v[36:37], v18, off

.LBB0_493:
	s_or_b64 exec, exec, s[8:9]
	v_bitop3_b32 v18, v68, s59, 35 bitop3:0xc8
	v_cvt_f32_u32_e32 v37, v18
	v_or_b32_e32 v36, v18, v69
	v_fmamk_f32 v57, v37, 0xbc44ade8, v90
	v_mul_f32_e64 v18, v91, |v57|
	v_mul_f32_e32 v18, 0x3fb8aa3b, v18
	v_exp_f32_e32 v18, v18
	v_ashrrev_i32_e32 v37, 31, v36
	v_lshlrev_b64 v[38:39], 14, v[36:37]
	v_add_f32_e32 v19, v19, v219
	v_mul_f32_e32 v36, v18, v19
	v_lshl_add_u64 v[18:19], s[6:7], 0, v[38:39]
	s_and_saveexec_b64 s[8:9], s[0:1]
	s_xor_b64 s[8:9], exec, s[8:9]
	s_cbranch_execz .LBB0_499
	s_and_saveexec_b64 s[10:11], s[4:5]
	s_xor_b64 s[10:11], exec, s[10:11]
	s_cbranch_execz .LBB0_496
	v_cvt_pk_bf16_f32 v38, v36, s0
	v_lshl_add_u64 v[36:37], v[66:67], 1, v[18:19]
	v_add_co_u32_e32 v36, vcc, 0x2000, v36
	s_nop 1
	v_addc_co_u32_e32 v37, vcc, 0, v37, vcc
	global_store_short v[36:37], v38, off

.LBB0_501:
	s_or_b64 exec, exec, s[8:9]
	v_bitop3_b32 v36, v68, s60, 40 bitop3:0xc8
	v_cvt_f32_u32_e32 v37, v36
	v_or_b32_e32 v36, v36, v69
	v_fmamk_f32 v59, v37, 0xbc44ade8, v90
	v_mul_f32_e64 v37, v91, |v59|
	v_mul_f32_e32 v37, 0x3fb8aa3b, v37
	v_exp_f32_e32 v38, v37
	v_ashrrev_i32_e32 v37, 31, v36
	v_lshlrev_b64 v[36:37], 14, v[36:37]
	v_lshl_add_u64 v[36:37], s[6:7], 0, v[36:37]
	v_add_f32_e32 v20, v20, v220
	v_mul_f32_e32 v20, v38, v20
	s_and_saveexec_b64 s[8:9], s[0:1]
	s_xor_b64 s[8:9], exec, s[8:9]
	s_cbranch_execz .LBB0_507
	s_and_saveexec_b64 s[10:11], s[4:5]
	s_xor_b64 s[10:11], exec, s[10:11]
	s_cbranch_execz .LBB0_504
	v_lshl_add_u64 v[38:39], v[66:67], 1, v[36:37]
	v_add_co_u32_e32 v38, vcc, 0x2000, v38
	v_cvt_pk_bf16_f32 v20, v20, s0
	s_nop 0
	v_addc_co_u32_e32 v39, vcc, 0, v39, vcc
	global_store_short v[38:39], v20, off

.LBB0_509:
	s_or_b64 exec, exec, s[8:9]
	v_bitop3_b32 v20, v68, s61, 41 bitop3:0xc8
	v_cvt_f32_u32_e32 v39, v20
	v_or_b32_e32 v38, v20, v69
	v_fmamk_f32 v61, v39, 0xbc44ade8, v90
	v_mul_f32_e64 v20, v91, |v61|
	v_mul_f32_e32 v20, 0x3fb8aa3b, v20
	v_exp_f32_e32 v20, v20
	v_ashrrev_i32_e32 v39, 31, v38
	v_lshlrev_b64 v[40:41], 14, v[38:39]
	v_add_f32_e32 v21, v21, v221
	v_mul_f32_e32 v38, v20, v21
	v_lshl_add_u64 v[20:21], s[6:7], 0, v[40:41]
	s_and_saveexec_b64 s[8:9], s[0:1]
	s_xor_b64 s[8:9], exec, s[8:9]
	s_cbranch_execz .LBB0_515
	s_and_saveexec_b64 s[10:11], s[4:5]
	s_xor_b64 s[10:11], exec, s[10:11]
	s_cbranch_execz .LBB0_512
	v_cvt_pk_bf16_f32 v40, v38, s0
	v_lshl_add_u64 v[38:39], v[66:67], 1, v[20:21]
	v_add_co_u32_e32 v38, vcc, 0x2000, v38
	s_nop 1
	v_addc_co_u32_e32 v39, vcc, 0, v39, vcc
	global_store_short v[38:39], v40, off

.LBB0_517:
	s_or_b64 exec, exec, s[8:9]
	v_bitop3_b32 v38, v68, s62, 42 bitop3:0xc8
	v_cvt_f32_u32_e32 v39, v38
	v_or_b32_e32 v38, v38, v69
	v_fmamk_f32 v63, v39, 0xbc44ade8, v90
	v_mul_f32_e64 v39, v91, |v63|
	v_mul_f32_e32 v39, 0x3fb8aa3b, v39
	v_exp_f32_e32 v40, v39
	v_ashrrev_i32_e32 v39, 31, v38
	v_lshlrev_b64 v[38:39], 14, v[38:39]
	v_lshl_add_u64 v[38:39], s[6:7], 0, v[38:39]
	v_add_f32_e32 v22, v22, v222
	v_mul_f32_e32 v22, v40, v22
	s_and_saveexec_b64 s[8:9], s[0:1]
	s_xor_b64 s[8:9], exec, s[8:9]
	s_cbranch_execz .LBB0_523
	s_and_saveexec_b64 s[10:11], s[4:5]
	s_xor_b64 s[10:11], exec, s[10:11]
	s_cbranch_execz .LBB0_520
	v_lshl_add_u64 v[40:41], v[66:67], 1, v[38:39]
	v_add_co_u32_e32 v40, vcc, 0x2000, v40
	v_cvt_pk_bf16_f32 v22, v22, s0
	s_nop 0
	v_addc_co_u32_e32 v41, vcc, 0, v41, vcc
	global_store_short v[40:41], v22, off

.LBB0_525:
	s_or_b64 exec, exec, s[8:9]
	v_bitop3_b32 v22, v68, s63, 43 bitop3:0xc8
	v_cvt_f32_u32_e32 v41, v22
	v_or_b32_e32 v40, v22, v69
	v_fmamk_f32 v73, v41, 0xbc44ade8, v90
	v_mul_f32_e64 v22, v91, |v73|
	v_mul_f32_e32 v22, 0x3fb8aa3b, v22
	v_exp_f32_e32 v22, v22
	v_ashrrev_i32_e32 v41, 31, v40
	v_lshlrev_b64 v[42:43], 14, v[40:41]
	v_add_f32_e32 v23, v23, v223
	v_mul_f32_e32 v40, v22, v23
	v_lshl_add_u64 v[22:23], s[6:7], 0, v[42:43]
	s_and_saveexec_b64 s[8:9], s[0:1]
	s_xor_b64 s[8:9], exec, s[8:9]
	s_cbranch_execz .LBB0_531
	s_and_saveexec_b64 s[10:11], s[4:5]
	s_xor_b64 s[10:11], exec, s[10:11]
	s_cbranch_execz .LBB0_528
	v_cvt_pk_bf16_f32 v42, v40, s0
	v_lshl_add_u64 v[40:41], v[66:67], 1, v[22:23]
	v_add_co_u32_e32 v40, vcc, 0x2000, v40
	s_nop 1
	v_addc_co_u32_e32 v41, vcc, 0, v41, vcc
	global_store_short v[40:41], v42, off

.LBB0_533:
	s_or_b64 exec, exec, s[8:9]
	v_bitop3_b32 v40, v68, s66, 48 bitop3:0xc8
	v_cvt_f32_u32_e32 v41, v40
	v_or_b32_e32 v40, v40, v69
	v_fmamk_f32 v75, v41, 0xbc44ade8, v90
	v_mul_f32_e64 v41, v91, |v75|
	v_mul_f32_e32 v41, 0x3fb8aa3b, v41
	v_exp_f32_e32 v42, v41
	v_ashrrev_i32_e32 v41, 31, v40
	v_lshlrev_b64 v[40:41], 14, v[40:41]
	v_lshl_add_u64 v[40:41], s[6:7], 0, v[40:41]
	v_add_f32_e32 v24, v24, v224
	v_mul_f32_e32 v24, v42, v24
	s_and_saveexec_b64 s[8:9], s[0:1]
	s_xor_b64 s[8:9], exec, s[8:9]
	s_cbranch_execz .LBB0_539
	s_and_saveexec_b64 s[10:11], s[4:5]
	s_xor_b64 s[10:11], exec, s[10:11]
	s_cbranch_execz .LBB0_536
	v_lshl_add_u64 v[42:43], v[66:67], 1, v[40:41]
	v_add_co_u32_e32 v42, vcc, 0x2000, v42
	v_cvt_pk_bf16_f32 v24, v24, s0
	s_nop 0
	v_addc_co_u32_e32 v43, vcc, 0, v43, vcc
	global_store_short v[42:43], v24, off

.LBB0_541:
	s_or_b64 exec, exec, s[8:9]
	v_bitop3_b32 v24, v68, s67, 49 bitop3:0xc8
	v_cvt_f32_u32_e32 v43, v24
	v_or_b32_e32 v42, v24, v69
	v_fmamk_f32 v77, v43, 0xbc44ade8, v90
	v_mul_f32_e64 v24, v91, |v77|
	v_mul_f32_e32 v24, 0x3fb8aa3b, v24
	v_exp_f32_e32 v24, v24
	v_ashrrev_i32_e32 v43, 31, v42
	v_lshlrev_b64 v[44:45], 14, v[42:43]
	v_add_f32_e32 v25, v25, v225
	v_mul_f32_e32 v42, v24, v25
	v_lshl_add_u64 v[24:25], s[6:7], 0, v[44:45]
	s_and_saveexec_b64 s[8:9], s[0:1]
	s_xor_b64 s[8:9], exec, s[8:9]
	s_cbranch_execz .LBB0_547
	s_and_saveexec_b64 s[10:11], s[4:5]
	s_xor_b64 s[10:11], exec, s[10:11]
	s_cbranch_execz .LBB0_544
	v_cvt_pk_bf16_f32 v44, v42, s0
	v_lshl_add_u64 v[42:43], v[66:67], 1, v[24:25]
	v_add_co_u32_e32 v42, vcc, 0x2000, v42
	s_nop 1
	v_addc_co_u32_e32 v43, vcc, 0, v43, vcc
	global_store_short v[42:43], v44, off

.LBB0_549:
	s_or_b64 exec, exec, s[8:9]
	v_bitop3_b32 v42, v68, s68, 50 bitop3:0xc8
	v_cvt_f32_u32_e32 v43, v42
	v_or_b32_e32 v42, v42, v69
	v_fmamk_f32 v79, v43, 0xbc44ade8, v90
	v_mul_f32_e64 v43, v91, |v79|
	v_mul_f32_e32 v43, 0x3fb8aa3b, v43
	v_exp_f32_e32 v44, v43
	v_ashrrev_i32_e32 v43, 31, v42
	v_lshlrev_b64 v[42:43], 14, v[42:43]
	v_lshl_add_u64 v[42:43], s[6:7], 0, v[42:43]
	v_add_f32_e32 v26, v26, v226
	v_mul_f32_e32 v26, v44, v26
	s_and_saveexec_b64 s[8:9], s[0:1]
	s_xor_b64 s[8:9], exec, s[8:9]
	s_cbranch_execz .LBB0_555
	s_and_saveexec_b64 s[10:11], s[4:5]
	s_xor_b64 s[10:11], exec, s[10:11]
	s_cbranch_execz .LBB0_552
	v_lshl_add_u64 v[44:45], v[66:67], 1, v[42:43]
	v_add_co_u32_e32 v44, vcc, 0x2000, v44
	v_cvt_pk_bf16_f32 v26, v26, s0
	s_nop 0
	v_addc_co_u32_e32 v45, vcc, 0, v45, vcc
	global_store_short v[44:45], v26, off

.LBB0_557:
	s_or_b64 exec, exec, s[8:9]
	v_bitop3_b32 v26, v68, s69, 51 bitop3:0xc8
	v_cvt_f32_u32_e32 v45, v26
	v_or_b32_e32 v44, v26, v69
	v_fmamk_f32 v81, v45, 0xbc44ade8, v90
	v_mul_f32_e64 v26, v91, |v81|
	v_mul_f32_e32 v26, 0x3fb8aa3b, v26
	v_exp_f32_e32 v26, v26
	v_ashrrev_i32_e32 v45, 31, v44
	v_lshlrev_b64 v[46:47], 14, v[44:45]
	v_add_f32_e32 v27, v27, v227
	v_mul_f32_e32 v44, v26, v27
	v_lshl_add_u64 v[26:27], s[6:7], 0, v[46:47]
	s_and_saveexec_b64 s[8:9], s[0:1]
	s_xor_b64 s[8:9], exec, s[8:9]
	s_cbranch_execz .LBB0_563
	s_and_saveexec_b64 s[10:11], s[4:5]
	s_xor_b64 s[10:11], exec, s[10:11]
	s_cbranch_execz .LBB0_560
	v_cvt_pk_bf16_f32 v46, v44, s0
	v_lshl_add_u64 v[44:45], v[66:67], 1, v[26:27]
	v_add_co_u32_e32 v44, vcc, 0x2000, v44
	s_nop 1
	v_addc_co_u32_e32 v45, vcc, 0, v45, vcc
	global_store_short v[44:45], v46, off

.LBB0_565:
	s_or_b64 exec, exec, s[8:9]
	v_bitop3_b32 v44, v68, s72, 56 bitop3:0xc8
	v_cvt_f32_u32_e32 v45, v44
	v_or_b32_e32 v44, v44, v69
	v_fmamk_f32 v83, v45, 0xbc44ade8, v90
	v_mul_f32_e64 v45, v91, |v83|
	v_mul_f32_e32 v45, 0x3fb8aa3b, v45
	v_exp_f32_e32 v46, v45
	v_ashrrev_i32_e32 v45, 31, v44
	v_lshlrev_b64 v[44:45], 14, v[44:45]
	v_lshl_add_u64 v[44:45], s[6:7], 0, v[44:45]
	v_add_f32_e32 v28, v28, v228
	v_mul_f32_e32 v28, v46, v28
	s_and_saveexec_b64 s[8:9], s[0:1]
	s_xor_b64 s[8:9], exec, s[8:9]
	s_cbranch_execz .LBB0_571
	s_and_saveexec_b64 s[10:11], s[4:5]
	s_xor_b64 s[10:11], exec, s[10:11]
	s_cbranch_execz .LBB0_568
	v_lshl_add_u64 v[46:47], v[66:67], 1, v[44:45]
	v_add_co_u32_e32 v46, vcc, 0x2000, v46
	v_cvt_pk_bf16_f32 v28, v28, s0
	s_nop 0
	v_addc_co_u32_e32 v47, vcc, 0, v47, vcc
	global_store_short v[46:47], v28, off

.LBB0_573:
	s_or_b64 exec, exec, s[8:9]
	v_bitop3_b32 v28, v68, s73, 57 bitop3:0xc8
	v_cvt_f32_u32_e32 v47, v28
	v_or_b32_e32 v46, v28, v69
	v_fmamk_f32 v85, v47, 0xbc44ade8, v90
	v_mul_f32_e64 v28, v91, |v85|
	v_mul_f32_e32 v28, 0x3fb8aa3b, v28
	v_exp_f32_e32 v28, v28
	v_ashrrev_i32_e32 v47, 31, v46
	v_lshlrev_b64 v[86:87], 14, v[46:47]
	v_add_f32_e32 v29, v29, v229
	v_mul_f32_e32 v46, v28, v29
	v_lshl_add_u64 v[28:29], s[6:7], 0, v[86:87]
	s_and_saveexec_b64 s[8:9], s[0:1]
	s_xor_b64 s[8:9], exec, s[8:9]
	s_cbranch_execz .LBB0_579
	s_and_saveexec_b64 s[10:11], s[4:5]
	s_xor_b64 s[10:11], exec, s[10:11]
	s_cbranch_execz .LBB0_576
	v_cvt_pk_bf16_f32 v86, v46, s0
	v_lshl_add_u64 v[46:47], v[66:67], 1, v[28:29]
	v_add_co_u32_e32 v46, vcc, 0x2000, v46
	s_nop 1
	v_addc_co_u32_e32 v47, vcc, 0, v47, vcc
	global_store_short v[46:47], v86, off

.LBB0_581:
	s_or_b64 exec, exec, s[8:9]
	v_bitop3_b32 v46, v68, s80, 58 bitop3:0xc8
	v_cvt_f32_u32_e32 v47, v46
	v_or_b32_e32 v46, v46, v69
	v_fmamk_f32 v87, v47, 0xbc44ade8, v90
	v_mul_f32_e64 v47, v91, |v87|
	v_mul_f32_e32 v47, 0x3fb8aa3b, v47
	v_exp_f32_e32 v88, v47
	v_ashrrev_i32_e32 v47, 31, v46
	v_lshlrev_b64 v[46:47], 14, v[46:47]
	v_lshl_add_u64 v[46:47], s[6:7], 0, v[46:47]
	v_add_f32_e32 v30, v30, v230
	v_mul_f32_e32 v30, v88, v30
	s_and_saveexec_b64 s[8:9], s[0:1]
	s_xor_b64 s[8:9], exec, s[8:9]
	s_cbranch_execz .LBB0_587
	s_and_saveexec_b64 s[10:11], s[4:5]
	s_xor_b64 s[10:11], exec, s[10:11]
	s_cbranch_execz .LBB0_584
	v_lshl_add_u64 v[88:89], v[66:67], 1, v[46:47]
	v_add_co_u32_e32 v88, vcc, 0x2000, v88
	v_cvt_pk_bf16_f32 v30, v30, s0
	s_nop 0
	v_addc_co_u32_e32 v89, vcc, 0, v89, vcc
	global_store_short v[88:89], v30, off

.LBB0_589:
	s_or_b64 exec, exec, s[8:9]
	v_bitop3_b32 v30, v68, s81, 59 bitop3:0xc8
	v_cvt_f32_u32_e32 v68, v30
	v_or_b32_e32 v88, v30, v69
	v_ashrrev_i32_e32 v89, 31, v88
	v_lshlrev_b64 v[88:89], 14, v[88:89]
	v_fmamk_f32 v68, v68, 0xbc44ade8, v90
	v_mul_f32_e64 v30, v91, |v68|
	v_mul_f32_e32 v30, 0x3fb8aa3b, v30
	v_exp_f32_e32 v30, v30
	v_add_f32_e32 v31, v31, v231
	v_mul_f32_e32 v69, v30, v31
	v_lshl_add_u64 v[30:31], s[6:7], 0, v[88:89]
	s_and_saveexec_b64 s[8:9], s[0:1]
	s_xor_b64 s[8:9], exec, s[8:9]
	s_cbranch_execz .LBB0_595
	s_and_saveexec_b64 s[10:11], s[4:5]
	s_xor_b64 s[4:5], exec, s[10:11]
	s_cbranch_execz .LBB0_592
	v_lshl_add_u64 v[88:89], v[66:67], 1, v[30:31]
	v_add_co_u32_e32 v88, vcc, 0x2000, v88
	v_cvt_pk_bf16_f32 v64, v69, s0
	s_nop 0
	v_addc_co_u32_e32 v89, vcc, 0, v89, vcc
	global_store_short v[88:89], v64, off

.LBB0_597:
	s_or_b64 exec, exec, s[4:5]
	v_mul_f32_e64 v51, v92, |v51|
	v_mul_f32_e32 v51, 0x3fb8aa3b, v51
	v_exp_f32_e32 v51, v51
	v_add_f32_e32 v0, v0, v216
	v_mul_f32_e32 v0, v51, v0
	v_cvt_pk_bf16_f32 v0, v0, s0
	s_and_saveexec_b64 s[4:5], s[0:1]
	s_xor_b64 s[4:5], exec, s[4:5]
	s_cbranch_execz .LBB0_599
	v_lshl_add_u64 v[32:33], v[66:67], 1, v[32:33]
	v_add_co_u32_e32 v32, vcc, 0x2000, v32
	s_nop 1
	v_addc_co_u32_e32 v33, vcc, 0, v33, vcc
	global_store_short v[32:33], v0, off offset:64

.LBB0_601:
	s_or_b64 exec, exec, s[4:5]
	v_mul_f32_e64 v0, v92, |v53|
	v_mul_f32_e32 v0, 0x3fb8aa3b, v0
	v_exp_f32_e32 v0, v0
	v_add_f32_e32 v1, v1, v217
	v_mul_f32_e32 v0, v0, v1
	v_cvt_pk_bf16_f32 v0, v0, s0
	s_and_saveexec_b64 s[4:5], s[0:1]
	s_xor_b64 s[4:5], exec, s[4:5]
	s_cbranch_execz .LBB0_603
	v_lshl_add_u64 v[16:17], v[66:67], 1, v[16:17]
	v_add_co_u32_e32 v16, vcc, 0x2000, v16
	s_nop 1
	v_addc_co_u32_e32 v17, vcc, 0, v17, vcc
	global_store_short v[16:17], v0, off offset:64

.LBB0_605:
	s_or_b64 exec, exec, s[4:5]
	v_mul_f32_e64 v0, v92, |v55|
	v_mul_f32_e32 v0, 0x3fb8aa3b, v0
	v_exp_f32_e32 v0, v0
	v_add_f32_e32 v1, v2, v218
	v_mul_f32_e32 v0, v0, v1
	v_cvt_pk_bf16_f32 v0, v0, s0
	s_and_saveexec_b64 s[4:5], s[0:1]
	s_xor_b64 s[4:5], exec, s[4:5]
	s_cbranch_execz .LBB0_607
	v_lshl_add_u64 v[16:17], v[66:67], 1, v[34:35]
	v_add_co_u32_e32 v16, vcc, 0x2000, v16
	s_nop 1
	v_addc_co_u32_e32 v17, vcc, 0, v17, vcc
	global_store_short v[16:17], v0, off offset:64

.LBB0_609:
	s_or_b64 exec, exec, s[4:5]
	v_mul_f32_e64 v0, v92, |v57|
	v_mul_f32_e32 v0, 0x3fb8aa3b, v0
	v_exp_f32_e32 v0, v0
	v_add_f32_e32 v1, v3, v219
	v_mul_f32_e32 v0, v0, v1
	v_cvt_pk_bf16_f32 v0, v0, s0
	s_and_saveexec_b64 s[4:5], s[0:1]
	s_xor_b64 s[4:5], exec, s[4:5]
	s_cbranch_execz .LBB0_611
	v_lshl_add_u64 v[2:3], v[66:67], 1, v[18:19]
	v_add_co_u32_e32 v2, vcc, 0x2000, v2
	s_nop 1
	v_addc_co_u32_e32 v3, vcc, 0, v3, vcc
	global_store_short v[2:3], v0, off offset:64

.LBB0_613:
	s_or_b64 exec, exec, s[4:5]
	v_mul_f32_e64 v0, v92, |v59|
	v_mul_f32_e32 v0, 0x3fb8aa3b, v0
	v_exp_f32_e32 v0, v0
	v_add_f32_e32 v1, v4, v220
	v_mul_f32_e32 v0, v0, v1
	v_cvt_pk_bf16_f32 v0, v0, s0
	s_and_saveexec_b64 s[4:5], s[0:1]
	s_xor_b64 s[4:5], exec, s[4:5]
	s_cbranch_execz .LBB0_615
	v_lshl_add_u64 v[2:3], v[66:67], 1, v[36:37]
	v_add_co_u32_e32 v2, vcc, 0x2000, v2
	s_nop 1
	v_addc_co_u32_e32 v3, vcc, 0, v3, vcc
	global_store_short v[2:3], v0, off offset:64

.LBB0_617:
	s_or_b64 exec, exec, s[4:5]
	v_mul_f32_e64 v0, v92, |v61|
	v_mul_f32_e32 v0, 0x3fb8aa3b, v0
	v_exp_f32_e32 v0, v0
	v_add_f32_e32 v1, v5, v221
	v_mul_f32_e32 v0, v0, v1
	v_cvt_pk_bf16_f32 v0, v0, s0
	s_and_saveexec_b64 s[4:5], s[0:1]
	s_xor_b64 s[4:5], exec, s[4:5]
	s_cbranch_execz .LBB0_619
	v_lshl_add_u64 v[2:3], v[66:67], 1, v[20:21]
	v_add_co_u32_e32 v2, vcc, 0x2000, v2
	s_nop 1
	v_addc_co_u32_e32 v3, vcc, 0, v3, vcc
	global_store_short v[2:3], v0, off offset:64

.LBB0_621:
	s_or_b64 exec, exec, s[4:5]
	v_mul_f32_e64 v0, v92, |v63|
	v_mul_f32_e32 v0, 0x3fb8aa3b, v0
	v_exp_f32_e32 v0, v0
	v_add_f32_e32 v1, v6, v222
	v_mul_f32_e32 v0, v0, v1
	v_cvt_pk_bf16_f32 v0, v0, s0
	s_and_saveexec_b64 s[4:5], s[0:1]
	s_xor_b64 s[4:5], exec, s[4:5]
	s_cbranch_execz .LBB0_623
	v_lshl_add_u64 v[2:3], v[66:67], 1, v[38:39]
	v_add_co_u32_e32 v2, vcc, 0x2000, v2
	s_nop 1
	v_addc_co_u32_e32 v3, vcc, 0, v3, vcc
	global_store_short v[2:3], v0, off offset:64

.LBB0_625:
	s_or_b64 exec, exec, s[4:5]
	v_mul_f32_e64 v0, v92, |v73|
	v_mul_f32_e32 v0, 0x3fb8aa3b, v0
	v_exp_f32_e32 v0, v0
	v_add_f32_e32 v1, v7, v223
	v_mul_f32_e32 v0, v0, v1
	v_cvt_pk_bf16_f32 v0, v0, s0
	s_and_saveexec_b64 s[4:5], s[0:1]
	s_xor_b64 s[4:5], exec, s[4:5]
	s_cbranch_execz .LBB0_627
	v_lshl_add_u64 v[2:3], v[66:67], 1, v[22:23]
	v_add_co_u32_e32 v2, vcc, 0x2000, v2
	s_nop 1
	v_addc_co_u32_e32 v3, vcc, 0, v3, vcc
	global_store_short v[2:3], v0, off offset:64

.LBB0_629:
	s_or_b64 exec, exec, s[4:5]
	v_mul_f32_e64 v0, v92, |v75|
	v_mul_f32_e32 v0, 0x3fb8aa3b, v0
	v_exp_f32_e32 v0, v0
	v_add_f32_e32 v1, v8, v224
	v_mul_f32_e32 v0, v0, v1
	v_cvt_pk_bf16_f32 v0, v0, s0
	s_and_saveexec_b64 s[4:5], s[0:1]
	s_xor_b64 s[4:5], exec, s[4:5]
	s_cbranch_execz .LBB0_631
	v_lshl_add_u64 v[2:3], v[66:67], 1, v[40:41]
	v_add_co_u32_e32 v2, vcc, 0x2000, v2
	s_nop 1
	v_addc_co_u32_e32 v3, vcc, 0, v3, vcc
	global_store_short v[2:3], v0, off offset:64

.LBB0_633:
	s_or_b64 exec, exec, s[4:5]
	v_mul_f32_e64 v0, v92, |v77|
	v_mul_f32_e32 v0, 0x3fb8aa3b, v0
	v_exp_f32_e32 v0, v0
	v_add_f32_e32 v1, v9, v225
	v_mul_f32_e32 v0, v0, v1
	v_cvt_pk_bf16_f32 v0, v0, s0
	s_and_saveexec_b64 s[4:5], s[0:1]
	s_xor_b64 s[4:5], exec, s[4:5]
	s_cbranch_execz .LBB0_635
	v_lshl_add_u64 v[2:3], v[66:67], 1, v[24:25]
	v_add_co_u32_e32 v2, vcc, 0x2000, v2
	s_nop 1
	v_addc_co_u32_e32 v3, vcc, 0, v3, vcc
	global_store_short v[2:3], v0, off offset:64

.LBB0_637:
	s_or_b64 exec, exec, s[4:5]
	v_mul_f32_e64 v0, v92, |v79|
	v_mul_f32_e32 v0, 0x3fb8aa3b, v0
	v_exp_f32_e32 v0, v0
	v_add_f32_e32 v1, v10, v226
	v_mul_f32_e32 v0, v0, v1
	v_cvt_pk_bf16_f32 v0, v0, s0
	s_and_saveexec_b64 s[4:5], s[0:1]
	s_xor_b64 s[4:5], exec, s[4:5]
	s_cbranch_execz .LBB0_639
	v_lshl_add_u64 v[2:3], v[66:67], 1, v[42:43]
	v_add_co_u32_e32 v2, vcc, 0x2000, v2
	s_nop 1
	v_addc_co_u32_e32 v3, vcc, 0, v3, vcc
	global_store_short v[2:3], v0, off offset:64

.LBB0_641:
	s_or_b64 exec, exec, s[4:5]
	v_mul_f32_e64 v0, v92, |v81|
	v_mul_f32_e32 v0, 0x3fb8aa3b, v0
	v_exp_f32_e32 v0, v0
	v_add_f32_e32 v1, v11, v227
	v_mul_f32_e32 v0, v0, v1
	v_cvt_pk_bf16_f32 v0, v0, s0
	s_and_saveexec_b64 s[4:5], s[0:1]
	s_xor_b64 s[4:5], exec, s[4:5]
	s_cbranch_execz .LBB0_643
	v_lshl_add_u64 v[2:3], v[66:67], 1, v[26:27]
	v_add_co_u32_e32 v2, vcc, 0x2000, v2
	s_nop 1
	v_addc_co_u32_e32 v3, vcc, 0, v3, vcc
	global_store_short v[2:3], v0, off offset:64

.LBB0_645:
	s_or_b64 exec, exec, s[4:5]
	v_mul_f32_e64 v0, v92, |v83|
	v_mul_f32_e32 v0, 0x3fb8aa3b, v0
	v_exp_f32_e32 v0, v0
	v_add_f32_e32 v1, v12, v228
	v_mul_f32_e32 v0, v0, v1
	v_cvt_pk_bf16_f32 v0, v0, s0
	s_and_saveexec_b64 s[4:5], s[0:1]
	s_xor_b64 s[4:5], exec, s[4:5]
	s_cbranch_execz .LBB0_647
	v_lshl_add_u64 v[2:3], v[66:67], 1, v[44:45]
	v_add_co_u32_e32 v2, vcc, 0x2000, v2
	s_nop 1
	v_addc_co_u32_e32 v3, vcc, 0, v3, vcc
	global_store_short v[2:3], v0, off offset:64

.LBB0_649:
	s_or_b64 exec, exec, s[4:5]
	v_mul_f32_e64 v0, v92, |v85|
	v_mul_f32_e32 v0, 0x3fb8aa3b, v0
	v_exp_f32_e32 v0, v0
	v_add_f32_e32 v1, v13, v229
	v_mul_f32_e32 v0, v0, v1
	v_cvt_pk_bf16_f32 v0, v0, s0
	s_and_saveexec_b64 s[4:5], s[0:1]
	s_xor_b64 s[4:5], exec, s[4:5]
	s_cbranch_execz .LBB0_651
	v_lshl_add_u64 v[2:3], v[66:67], 1, v[28:29]
	v_add_co_u32_e32 v2, vcc, 0x2000, v2
	s_nop 1
	v_addc_co_u32_e32 v3, vcc, 0, v3, vcc
	global_store_short v[2:3], v0, off offset:64

.LBB0_653:
	s_or_b64 exec, exec, s[4:5]
	v_mul_f32_e64 v0, v92, |v87|
	v_mul_f32_e32 v0, 0x3fb8aa3b, v0
	v_exp_f32_e32 v0, v0
	v_add_f32_e32 v1, v14, v230
	v_mul_f32_e32 v0, v0, v1
	v_cvt_pk_bf16_f32 v0, v0, s0
	s_and_saveexec_b64 s[4:5], s[0:1]
	s_xor_b64 s[4:5], exec, s[4:5]
	s_cbranch_execz .LBB0_655
	v_lshl_add_u64 v[2:3], v[66:67], 1, v[46:47]
	v_add_co_u32_e32 v2, vcc, 0x2000, v2
	s_nop 1
	v_addc_co_u32_e32 v3, vcc, 0, v3, vcc
	global_store_short v[2:3], v0, off offset:64

.LBB0_657:
	s_or_b64 exec, exec, s[4:5]
	v_mul_f32_e64 v0, v92, |v68|
	v_mul_f32_e32 v0, 0x3fb8aa3b, v0
	v_exp_f32_e32 v0, v0
	v_add_f32_e32 v1, v15, v231
	v_mul_f32_e32 v0, v0, v1
	v_cvt_pk_bf16_f32 v0, v0, s0
	s_and_saveexec_b64 s[4:5], s[0:1]
	s_xor_b64 s[0:1], exec, s[4:5]
	s_cbranch_execz .LBB0_659
	v_lshl_add_u64 v[2:3], v[66:67], 1, v[30:31]
	v_add_co_u32_e32 v2, vcc, 0x2000, v2
	s_nop 1
	v_addc_co_u32_e32 v3, vcc, 0, v3, vcc
	global_store_short v[2:3], v0, off offset:64
